# P7 SwiGLU epilogue: silu divide g/(1+exp(-g)) computed as g*v_rcp_f32(1+exp(-g)) in f32 instead of the 11-instruction IEEE division sequence; store-data hazard pad re-derived
# speedup vs baseline: 1.0332x; 1.0121x over previous
.LBB0_1301:
	v_mul_f32_e32 v162, 0xbfb8aa3b, v124
	v_exp_f32_e32 v163, v162
	v_lshl_or_b32 v164, s2, 7, v158
	v_mul_f32_e32 v170, 0xbfb8aa3b, v125
	v_exp_f32_e32 v170, v170
	v_add_f32_e32 v163, 1.0, v163
	v_lshl_add_u32 v162, s24, 8, v156
	v_add_f32_e32 v168, 1.0, v170
	v_rcp_f32_e32 v240, v163
	s_nop 0
	v_mul_f32_e32 v124, v124, v240
	v_mul_f32_e32 v120, v124, v120
	v_mul_f32_e32 v166, 0xbfb8aa3b, v126
	v_exp_f32_e32 v166, v166
	v_rcp_f32_e32 v240, v168
	s_nop 0
	v_mul_f32_e32 v124, v125, v240
	v_add_f32_e32 v163, 1.0, v166
	v_mul_f32_e32 v121, v124, v121
	v_mul_f32_e32 v125, 0xbfb8aa3b, v127
	v_cvt_pk_bf16_f32 v120, v120, v121
	v_exp_f32_e32 v125, v125
	s_nop 0
	v_add_f32_e32 v125, 1.0, v125
	v_rcp_f32_e32 v240, v163
	s_nop 0
	v_mul_f32_e32 v121, v126, v240
	v_mul_f32_e32 v121, v121, v122
	v_mul_f32_e32 v126, 0xbfb8aa3b, v116
	v_exp_f32_e32 v126, v126
	v_rcp_f32_e32 v240, v125
	s_nop 0
	v_mul_f32_e32 v122, v127, v240
	v_add_f32_e32 v124, 1.0, v126
	v_mul_f32_e32 v122, v122, v123
	v_mul_f32_e32 v125, 0xbfb8aa3b, v117
	v_cvt_pk_bf16_f32 v121, v121, v122
	v_exp_f32_e32 v125, v125
	s_nop 0
	v_add_f32_e32 v125, 1.0, v125
	v_rcp_f32_e32 v240, v124
	s_nop 0
	v_mul_f32_e32 v116, v116, v240
	v_mul_f32_e32 v112, v116, v112
	v_mul_f32_e32 v123, 0xbfb8aa3b, v118
	v_exp_f32_e32 v123, v123
	v_rcp_f32_e32 v240, v125
	s_nop 0
	v_mul_f32_e32 v116, v117, v240
	v_add_f32_e32 v123, 1.0, v123
	v_mul_f32_e32 v113, v116, v113
	v_mul_f32_e32 v116, 0xbfb8aa3b, v119
	v_exp_f32_e32 v116, v116
	v_cvt_pk_bf16_f32 v122, v112, v113
	v_add_f32_e32 v116, 1.0, v116
	v_rcp_f32_e32 v240, v123
	s_nop 0
	v_mul_f32_e32 v112, v118, v240
	v_mul_f32_e32 v112, v112, v114
	v_mul_f32_e32 v114, 0xbfb8aa3b, v108
	v_exp_f32_e32 v118, v114
	v_rcp_f32_e32 v240, v116
	s_nop 0
	v_mul_f32_e32 v113, v119, v240
	v_mul_f32_e32 v113, v113, v115
	v_ashrrev_i32_e32 v165, 31, v164
	v_add_f32_e32 v118, 1.0, v118
	v_cvt_pk_bf16_f32 v123, v112, v113
	v_mov_b64_e32 v[112:113], s[8:9]
	v_mad_i64_i32 v[116:117], s[2:3], v162, s45, v[112:113]
	v_lshlrev_b64 v[114:115], 1, v[164:165]
	v_lshl_add_u64 v[116:117], v[116:117], 0, v[114:115]
	global_store_dwordx4 v[116:117], v[120:123], off
	s_nop 1
	v_mul_f32_e32 v121, 0xbfb8aa3b, v109
	v_exp_f32_e32 v121, v121
	s_nop 0
	v_add_f32_e32 v119, 1.0, v121
	v_rcp_f32_e32 v240, v118
	s_nop 0
	v_mul_f32_e32 v108, v108, v240
	v_mul_f32_e32 v104, v108, v104
	v_mul_f32_e32 v118, 0xbfb8aa3b, v110
	v_exp_f32_e32 v118, v118
	v_rcp_f32_e32 v240, v119
	s_nop 0
	v_mul_f32_e32 v108, v109, v240
	v_add_f32_e32 v117, 1.0, v118
	v_mul_f32_e32 v105, v108, v105
	v_mul_f32_e32 v109, 0xbfb8aa3b, v111
	v_cvt_pk_bf16_f32 v104, v104, v105
	v_exp_f32_e32 v109, v109
	s_nop 0
	v_add_f32_e32 v109, 1.0, v109
	v_rcp_f32_e32 v240, v117
	s_nop 0
	v_mul_f32_e32 v105, v110, v240
	v_mul_f32_e32 v105, v105, v106
	v_mul_f32_e32 v110, 0xbfb8aa3b, v100
	v_exp_f32_e32 v110, v110
	v_rcp_f32_e32 v240, v109
	s_nop 0
	v_mul_f32_e32 v106, v111, v240
	v_add_f32_e32 v108, 1.0, v110
	v_mul_f32_e32 v106, v106, v107
	v_mul_f32_e32 v109, 0xbfb8aa3b, v101
	v_cvt_pk_bf16_f32 v105, v105, v106
	v_exp_f32_e32 v109, v109
	s_nop 0
	v_add_f32_e32 v109, 1.0, v109
	v_rcp_f32_e32 v240, v108
	s_nop 0
	v_mul_f32_e32 v100, v100, v240
	v_mul_f32_e32 v96, v100, v96
	v_mul_f32_e32 v107, 0xbfb8aa3b, v102
	v_exp_f32_e32 v107, v107
	v_rcp_f32_e32 v240, v109
	s_nop 0
	v_mul_f32_e32 v100, v101, v240
	v_add_f32_e32 v107, 1.0, v107
	v_mul_f32_e32 v97, v100, v97
	v_mul_f32_e32 v100, 0xbfb8aa3b, v103
	v_exp_f32_e32 v100, v100
	v_cvt_pk_bf16_f32 v106, v96, v97
	v_add_f32_e32 v100, 1.0, v100
	v_rcp_f32_e32 v240, v107
	s_nop 0
	v_mul_f32_e32 v96, v102, v240
	v_mul_f32_e32 v96, v96, v98
	v_mul_f32_e32 v98, 0xbfb8aa3b, v92
	v_exp_f32_e32 v98, v98
	v_rcp_f32_e32 v240, v100
	s_nop 0
	v_mul_f32_e32 v97, v103, v240
	v_mul_f32_e32 v97, v97, v99
	v_or_b32_e32 v116, 16, v162
	v_add_f32_e32 v98, 1.0, v98
	v_cvt_pk_bf16_f32 v107, v96, v97
	v_mad_i64_i32 v[96:97], s[2:3], v116, s45, v[112:113]
	v_lshl_add_u64 v[96:97], v[96:97], 0, v[114:115]
	global_store_dwordx4 v[96:97], v[104:107], off
	v_mul_f32_e32 v102, 0xbfb8aa3b, v93
	v_exp_f32_e32 v102, v102
	s_nop 0
	v_add_f32_e32 v99, 1.0, v102
	v_rcp_f32_e32 v240, v98
	s_nop 0
	v_mul_f32_e32 v92, v92, v240
	v_mul_f32_e32 v88, v92, v88
	v_mul_f32_e32 v98, 0xbfb8aa3b, v94
	v_exp_f32_e32 v98, v98
	v_rcp_f32_e32 v240, v99
	s_nop 0
	v_mul_f32_e32 v92, v93, v240
	v_add_f32_e32 v97, 1.0, v98
	v_mul_f32_e32 v89, v92, v89
	v_mul_f32_e32 v93, 0xbfb8aa3b, v95
	v_cvt_pk_bf16_f32 v88, v88, v89
	v_exp_f32_e32 v93, v93
	s_nop 0
	v_add_f32_e32 v93, 1.0, v93
	v_rcp_f32_e32 v240, v97
	s_nop 0
	v_mul_f32_e32 v89, v94, v240
	v_mul_f32_e32 v89, v89, v90
	v_mul_f32_e32 v94, 0xbfb8aa3b, v84
	v_exp_f32_e32 v94, v94
	v_rcp_f32_e32 v240, v93
	s_nop 0
	v_mul_f32_e32 v90, v95, v240
	v_add_f32_e32 v92, 1.0, v94
	v_mul_f32_e32 v90, v90, v91
	v_mul_f32_e32 v93, 0xbfb8aa3b, v85
	v_cvt_pk_bf16_f32 v89, v89, v90
	v_exp_f32_e32 v93, v93
	s_nop 0
	v_add_f32_e32 v93, 1.0, v93
	v_rcp_f32_e32 v240, v92
	s_nop 0
	v_mul_f32_e32 v84, v84, v240
	v_mul_f32_e32 v80, v84, v80
	v_mul_f32_e32 v91, 0xbfb8aa3b, v86
	v_exp_f32_e32 v91, v91
	v_rcp_f32_e32 v240, v93
	s_nop 0
	v_mul_f32_e32 v84, v85, v240
	v_add_f32_e32 v91, 1.0, v91
	v_mul_f32_e32 v81, v84, v81
	v_mul_f32_e32 v84, 0xbfb8aa3b, v87
	v_exp_f32_e32 v84, v84
	v_cvt_pk_bf16_f32 v90, v80, v81
	v_add_f32_e32 v84, 1.0, v84
	v_rcp_f32_e32 v240, v91
	s_nop 0
	v_mul_f32_e32 v80, v86, v240
	v_mul_f32_e32 v80, v80, v82
	v_mul_f32_e32 v82, 0xbfb8aa3b, v76
	v_exp_f32_e32 v82, v82
	v_rcp_f32_e32 v240, v84
	s_nop 0
	v_mul_f32_e32 v81, v87, v240
	v_mul_f32_e32 v81, v81, v83
	v_or_b32_e32 v96, 32, v162
	v_add_f32_e32 v82, 1.0, v82
	v_cvt_pk_bf16_f32 v91, v80, v81
	v_mad_i64_i32 v[80:81], s[2:3], v96, s45, v[112:113]
	v_lshl_add_u64 v[80:81], v[80:81], 0, v[114:115]
	global_store_dwordx4 v[80:81], v[88:91], off
	v_mul_f32_e32 v86, 0xbfb8aa3b, v77
	v_exp_f32_e32 v86, v86
	s_nop 0
	v_add_f32_e32 v83, 1.0, v86
	v_rcp_f32_e32 v240, v82
	s_nop 0
	v_mul_f32_e32 v76, v76, v240
	v_mul_f32_e32 v72, v76, v72
	v_mul_f32_e32 v82, 0xbfb8aa3b, v78
	v_exp_f32_e32 v82, v82
	v_rcp_f32_e32 v240, v83
	s_nop 0
	v_mul_f32_e32 v76, v77, v240
	v_add_f32_e32 v81, 1.0, v82
	v_mul_f32_e32 v73, v76, v73
	v_mul_f32_e32 v77, 0xbfb8aa3b, v79
	v_cvt_pk_bf16_f32 v72, v72, v73
	v_exp_f32_e32 v77, v77
	s_nop 0
	v_add_f32_e32 v77, 1.0, v77
	v_rcp_f32_e32 v240, v81
	s_nop 0
	v_mul_f32_e32 v73, v78, v240
	v_mul_f32_e32 v73, v73, v74
	v_mul_f32_e32 v78, 0xbfb8aa3b, v68
	v_exp_f32_e32 v78, v78
	v_rcp_f32_e32 v240, v77
	s_nop 0
	v_mul_f32_e32 v74, v79, v240
	v_add_f32_e32 v76, 1.0, v78
	v_mul_f32_e32 v74, v74, v75
	v_mul_f32_e32 v77, 0xbfb8aa3b, v69
	v_cvt_pk_bf16_f32 v73, v73, v74
	v_exp_f32_e32 v77, v77
	s_nop 0
	v_add_f32_e32 v77, 1.0, v77
	v_rcp_f32_e32 v240, v76
	s_nop 0
	v_mul_f32_e32 v68, v68, v240
	v_mul_f32_e32 v64, v68, v64
	v_mul_f32_e32 v75, 0xbfb8aa3b, v70
	v_exp_f32_e32 v75, v75
	v_rcp_f32_e32 v240, v77
	s_nop 0
	v_mul_f32_e32 v68, v69, v240
	v_add_f32_e32 v75, 1.0, v75
	v_mul_f32_e32 v65, v68, v65
	v_mul_f32_e32 v68, 0xbfb8aa3b, v71
	v_exp_f32_e32 v68, v68
	v_cvt_pk_bf16_f32 v74, v64, v65
	v_add_f32_e32 v68, 1.0, v68
	v_rcp_f32_e32 v240, v75
	s_nop 0
	v_mul_f32_e32 v64, v70, v240
	v_mul_f32_e32 v64, v64, v66
	v_mul_f32_e32 v66, 0xbfb8aa3b, v60
	v_exp_f32_e32 v66, v66
	v_rcp_f32_e32 v240, v68
	s_nop 0
	v_mul_f32_e32 v65, v71, v240
	v_mul_f32_e32 v65, v65, v67
	v_or_b32_e32 v80, 48, v162
	v_add_f32_e32 v66, 1.0, v66
	v_cvt_pk_bf16_f32 v75, v64, v65
	v_mad_i64_i32 v[64:65], s[2:3], v80, s45, v[112:113]
	v_lshl_add_u64 v[64:65], v[64:65], 0, v[114:115]
	global_store_dwordx4 v[64:65], v[72:75], off
	v_mul_f32_e32 v70, 0xbfb8aa3b, v61
	v_exp_f32_e32 v70, v70
	s_nop 0
	v_add_f32_e32 v67, 1.0, v70
	v_rcp_f32_e32 v240, v66
	s_nop 0
	v_mul_f32_e32 v60, v60, v240
	v_mul_f32_e32 v56, v60, v56
	v_mul_f32_e32 v66, 0xbfb8aa3b, v62
	v_exp_f32_e32 v66, v66
	v_rcp_f32_e32 v240, v67
	s_nop 0
	v_mul_f32_e32 v60, v61, v240
	v_add_f32_e32 v65, 1.0, v66
	v_mul_f32_e32 v57, v60, v57
	v_mul_f32_e32 v61, 0xbfb8aa3b, v63
	v_cvt_pk_bf16_f32 v56, v56, v57
	v_exp_f32_e32 v61, v61
	s_nop 0
	v_add_f32_e32 v61, 1.0, v61
	v_rcp_f32_e32 v240, v65
	s_nop 0
	v_mul_f32_e32 v57, v62, v240
	v_mul_f32_e32 v57, v57, v58
	v_mul_f32_e32 v62, 0xbfb8aa3b, v52
	v_exp_f32_e32 v62, v62
	v_rcp_f32_e32 v240, v61
	s_nop 0
	v_mul_f32_e32 v58, v63, v240
	v_add_f32_e32 v60, 1.0, v62
	v_mul_f32_e32 v58, v58, v59
	v_mul_f32_e32 v61, 0xbfb8aa3b, v53
	v_cvt_pk_bf16_f32 v57, v57, v58
	v_exp_f32_e32 v61, v61
	s_nop 0
	v_add_f32_e32 v61, 1.0, v61
	v_rcp_f32_e32 v240, v60
	s_nop 0
	v_mul_f32_e32 v52, v52, v240
	v_mul_f32_e32 v48, v52, v48
	v_mul_f32_e32 v59, 0xbfb8aa3b, v54
	v_exp_f32_e32 v59, v59
	v_rcp_f32_e32 v240, v61
	s_nop 0
	v_mul_f32_e32 v52, v53, v240
	v_add_f32_e32 v59, 1.0, v59
	v_mul_f32_e32 v49, v52, v49
	v_mul_f32_e32 v52, 0xbfb8aa3b, v55
	v_exp_f32_e32 v52, v52
	v_cvt_pk_bf16_f32 v58, v48, v49
	v_add_f32_e32 v52, 1.0, v52
	v_rcp_f32_e32 v240, v59
	s_nop 0
	v_mul_f32_e32 v48, v54, v240
	v_mul_f32_e32 v48, v48, v50
	v_mul_f32_e32 v50, 0xbfb8aa3b, v44
	v_exp_f32_e32 v50, v50
	v_rcp_f32_e32 v240, v52
	s_nop 0
	v_mul_f32_e32 v49, v55, v240
	v_mul_f32_e32 v49, v49, v51
	v_add_u32_e32 v64, 0x80, v162
	v_add_f32_e32 v50, 1.0, v50
	v_cvt_pk_bf16_f32 v59, v48, v49
	v_mad_i64_i32 v[48:49], s[2:3], v64, s45, v[112:113]
	v_lshl_add_u64 v[48:49], v[48:49], 0, v[114:115]
	global_store_dwordx4 v[48:49], v[56:59], off
	v_mul_f32_e32 v54, 0xbfb8aa3b, v45
	v_exp_f32_e32 v54, v54
	s_nop 0
	v_add_f32_e32 v51, 1.0, v54
	v_rcp_f32_e32 v240, v50
	s_nop 0
	v_mul_f32_e32 v44, v44, v240
	v_mul_f32_e32 v40, v44, v40
	v_mul_f32_e32 v50, 0xbfb8aa3b, v46
	v_exp_f32_e32 v50, v50
	v_rcp_f32_e32 v240, v51
	s_nop 0
	v_mul_f32_e32 v44, v45, v240
	v_add_f32_e32 v49, 1.0, v50
	v_mul_f32_e32 v41, v44, v41
	v_mul_f32_e32 v45, 0xbfb8aa3b, v47
	v_cvt_pk_bf16_f32 v40, v40, v41
	v_exp_f32_e32 v45, v45
	s_nop 0
	v_add_f32_e32 v45, 1.0, v45
	v_rcp_f32_e32 v240, v49
	s_nop 0
	v_mul_f32_e32 v41, v46, v240
	v_mul_f32_e32 v41, v41, v42
	v_mul_f32_e32 v46, 0xbfb8aa3b, v36
	v_exp_f32_e32 v46, v46
	v_rcp_f32_e32 v240, v45
	s_nop 0
	v_mul_f32_e32 v42, v47, v240
	v_add_f32_e32 v44, 1.0, v46
	v_mul_f32_e32 v42, v42, v43
	v_mul_f32_e32 v45, 0xbfb8aa3b, v37
	v_cvt_pk_bf16_f32 v41, v41, v42
	v_exp_f32_e32 v45, v45
	s_nop 0
	v_add_f32_e32 v45, 1.0, v45
	v_rcp_f32_e32 v240, v44
	s_nop 0
	v_mul_f32_e32 v36, v36, v240
	v_mul_f32_e32 v32, v36, v32
	v_mul_f32_e32 v43, 0xbfb8aa3b, v38
	v_exp_f32_e32 v43, v43
	v_rcp_f32_e32 v240, v45
	s_nop 0
	v_mul_f32_e32 v36, v37, v240
	v_add_f32_e32 v43, 1.0, v43
	v_mul_f32_e32 v33, v36, v33
	v_mul_f32_e32 v36, 0xbfb8aa3b, v39
	v_exp_f32_e32 v36, v36
	v_cvt_pk_bf16_f32 v42, v32, v33
	v_add_f32_e32 v36, 1.0, v36
	v_rcp_f32_e32 v240, v43
	s_nop 0
	v_mul_f32_e32 v32, v38, v240
	v_mul_f32_e32 v32, v32, v34
	v_mul_f32_e32 v34, 0xbfb8aa3b, v28
	v_exp_f32_e32 v34, v34
	v_rcp_f32_e32 v240, v36
	s_nop 0
	v_mul_f32_e32 v33, v39, v240
	v_mul_f32_e32 v33, v33, v35
	v_add_u32_e32 v48, 0x90, v162
	v_add_f32_e32 v34, 1.0, v34
	v_cvt_pk_bf16_f32 v43, v32, v33
	v_mad_i64_i32 v[32:33], s[2:3], v48, s45, v[112:113]
	v_lshl_add_u64 v[32:33], v[32:33], 0, v[114:115]
	global_store_dwordx4 v[32:33], v[40:43], off
	v_mul_f32_e32 v38, 0xbfb8aa3b, v29
	v_exp_f32_e32 v38, v38
	s_nop 0
	v_add_f32_e32 v35, 1.0, v38
	v_rcp_f32_e32 v240, v34
	s_nop 0
	v_mul_f32_e32 v28, v28, v240
	v_mul_f32_e32 v24, v28, v24
	v_mul_f32_e32 v34, 0xbfb8aa3b, v30
	v_exp_f32_e32 v34, v34
	v_rcp_f32_e32 v240, v35
	s_nop 0
	v_mul_f32_e32 v28, v29, v240
	v_add_f32_e32 v33, 1.0, v34
	v_mul_f32_e32 v25, v28, v25
	v_mul_f32_e32 v29, 0xbfb8aa3b, v31
	v_cvt_pk_bf16_f32 v24, v24, v25
	v_exp_f32_e32 v29, v29
	s_nop 0
	v_add_f32_e32 v29, 1.0, v29
	v_rcp_f32_e32 v240, v33
	s_nop 0
	v_mul_f32_e32 v25, v30, v240
	v_mul_f32_e32 v25, v25, v26
	v_mul_f32_e32 v30, 0xbfb8aa3b, v20
	v_exp_f32_e32 v30, v30
	v_rcp_f32_e32 v240, v29
	s_nop 0
	v_mul_f32_e32 v26, v31, v240
	v_add_f32_e32 v28, 1.0, v30
	v_mul_f32_e32 v26, v26, v27
	v_mul_f32_e32 v29, 0xbfb8aa3b, v21
	v_cvt_pk_bf16_f32 v25, v25, v26
	v_exp_f32_e32 v29, v29
	s_nop 0
	v_add_f32_e32 v29, 1.0, v29
	v_rcp_f32_e32 v240, v28
	s_nop 0
	v_mul_f32_e32 v20, v20, v240
	v_mul_f32_e32 v16, v20, v16
	v_mul_f32_e32 v27, 0xbfb8aa3b, v22
	v_exp_f32_e32 v27, v27
	v_rcp_f32_e32 v240, v29
	s_nop 0
	v_mul_f32_e32 v20, v21, v240
	v_add_f32_e32 v27, 1.0, v27
	v_mul_f32_e32 v17, v20, v17
	v_mul_f32_e32 v20, 0xbfb8aa3b, v23
	v_exp_f32_e32 v20, v20
	v_cvt_pk_bf16_f32 v26, v16, v17
	v_add_f32_e32 v20, 1.0, v20
	v_rcp_f32_e32 v240, v27
	s_nop 0
	v_mul_f32_e32 v16, v22, v240
	v_mul_f32_e32 v16, v16, v18
	v_mul_f32_e32 v18, 0xbfb8aa3b, v12
	v_exp_f32_e32 v18, v18
	v_rcp_f32_e32 v240, v20
	s_nop 0
	v_mul_f32_e32 v17, v23, v240
	v_mul_f32_e32 v17, v17, v19
	v_add_u32_e32 v32, 0xa0, v162
	v_add_f32_e32 v18, 1.0, v18
	v_cvt_pk_bf16_f32 v27, v16, v17
	v_mad_i64_i32 v[16:17], s[2:3], v32, s45, v[112:113]
	v_lshl_add_u64 v[16:17], v[16:17], 0, v[114:115]
	global_store_dwordx4 v[16:17], v[24:27], off
	v_mul_f32_e32 v22, 0xbfb8aa3b, v13
	v_exp_f32_e32 v22, v22
	s_nop 0
	v_add_f32_e32 v19, 1.0, v22
	v_rcp_f32_e32 v240, v18
	s_nop 0
	v_mul_f32_e32 v12, v12, v240
	v_mul_f32_e32 v8, v12, v8
	v_mul_f32_e32 v18, 0xbfb8aa3b, v14
	v_exp_f32_e32 v18, v18
	v_rcp_f32_e32 v240, v19
	s_nop 0
	v_mul_f32_e32 v12, v13, v240
	v_add_f32_e32 v17, 1.0, v18
	v_mul_f32_e32 v9, v12, v9
	v_mul_f32_e32 v13, 0xbfb8aa3b, v15
	v_cvt_pk_bf16_f32 v8, v8, v9
	v_exp_f32_e32 v13, v13
	s_nop 0
	v_add_f32_e32 v13, 1.0, v13
	v_rcp_f32_e32 v240, v17
	s_nop 0
	v_mul_f32_e32 v9, v14, v240
	v_mul_f32_e32 v9, v9, v10
	v_mul_f32_e32 v14, 0xbfb8aa3b, v4
	v_exp_f32_e32 v14, v14
	v_rcp_f32_e32 v240, v13
	s_nop 0
	v_mul_f32_e32 v10, v15, v240
	v_add_f32_e32 v12, 1.0, v14
	v_mul_f32_e32 v10, v10, v11
	v_mul_f32_e32 v13, 0xbfb8aa3b, v5
	v_cvt_pk_bf16_f32 v9, v9, v10
	v_exp_f32_e32 v13, v13
	s_nop 0
	v_add_f32_e32 v13, 1.0, v13
	v_rcp_f32_e32 v240, v12
	s_nop 0
	v_mul_f32_e32 v4, v4, v240
	v_mul_f32_e32 v0, v4, v0
	v_mul_f32_e32 v11, 0xbfb8aa3b, v6
	v_exp_f32_e32 v11, v11
	v_rcp_f32_e32 v240, v13
	s_nop 0
	v_mul_f32_e32 v4, v5, v240
	v_add_f32_e32 v11, 1.0, v11
	v_mul_f32_e32 v1, v4, v1
	v_mul_f32_e32 v4, 0xbfb8aa3b, v7
	v_exp_f32_e32 v4, v4
	v_cvt_pk_bf16_f32 v10, v0, v1
	v_add_f32_e32 v4, 1.0, v4
	v_rcp_f32_e32 v240, v11
	s_nop 0
	v_mul_f32_e32 v0, v6, v240
	v_mul_f32_e32 v0, v0, v2
	v_rcp_f32_e32 v240, v4
	s_nop 0
	v_mul_f32_e32 v1, v7, v240
	v_add_u32_e32 v16, 0xb0, v162
	v_mul_f32_e32 v1, v1, v3
	v_cvt_pk_bf16_f32 v11, v0, v1
	v_mad_i64_i32 v[0:1], s[2:3], v16, s45, v[112:113]
	v_lshl_add_u64 v[0:1], v[0:1], 0, v[114:115]
	s_andn2_b64 vcc, exec, s[0:1]
	s_mov_b64 s[0:1], -1
	global_store_dwordx4 v[0:1], v[8:11], off
	s_cbranch_vccnz .LBB0_1290
	s_andn2_b64 vcc, exec, s[10:11]
	s_cbranch_vccnz .LBB0_1289
	s_barrier
	s_branch .LBB0_1289
